# K and V fragment LDS reads hoisted ahead of bias math / right behind QK MFMAs in FoX-unmasked and slc tiles
# baseline (speedup 1.0000x reference)
; DI void qk_acc(lptr Kt, const bf16x8 (&qf)[4], f32x16& s0, f32x16& s1, int lane) {
;     const int i = lane & 31, hi = lane >> 5;
;     const int krow = (i & 19) | ((i & 4) << 1) | ((i & 8) >> 1);
;     lptr kp = Kt + krow * KPB + hi * 16;
;     bf16x8 a0[4], a1[4];
; #pragma unroll
;     for (int d0 = 0; d0 < 4; ++d0) { a0[d0] = *(LAS bf16x8*)(kp + d0 * 32); a1[d0] = *(LAS bf16x8*)(kp + 32 * KPB + d0 * 32); }
;     __builtin_amdgcn_s_setprio(1);
; template <int MODE>
; DI void bias_init(f32x16& s0, f32x16& s1, const TP& tp, float fbm, int hi) {
; #pragma unroll
;     for (int r = 0; r < 16; ++r) {
;         const int kvc = 16 * (r >> 3) + (r & 7);
;         if (MODE == 0) { s0[r] = __builtin_fmaf(-L2E, tp.cs[kvc + 8 * hi], fbm); s1[r] = __builtin_fmaf(-L2E, tp.cs[kvc + 32 + 8 * hi], fbm); }
;         else { s0[r] = __builtin_fmaf(tp.sl, (float)kvc, fbm); s1[r] = __builtin_fmaf(tp.sl, (float)(kvc + 32), fbm); }
;     }
; }
; DI float max3_asm(float a, float b, float c) { float r; asm("v_max3_f32 %0, %1, %2, %3" : "=v"(r) : "v"(a), "v"(b), "v"(c)); return r; }
; template <bool MASK>
; DI float mask_rowmax(f32x16& s0, f32x16& s1, const TP& tp) {
;     if (MASK) {
; #pragma unroll
;         for (int r = 0; r < 16; ++r) {
;             const int kvc = 16 * (r >> 3) + (r & 7);
;             const bool v0 = tp.sel && (kvc <= tp.lim) && (kvc > tp.lim2), v1 = tp.sel && (kvc + 32 <= tp.lim) && (kvc + 32 > tp.lim2);
;             s0[r] = v0 ? s0[r] : -1e30f; s1[r] = v1 ? s1[r] : -1e30f;
;         }
;     }
;     const float seed = __builtin_fminf(s0[15], s1[15]);
;     float ma = seed, mb = seed;
; #pragma unroll
;     for (int r = 0; r < 16; r += 2) { ma = max3_asm(ma, s0[r], s1[r]); mb = max3_asm(mb, s0[r + 1], s1[r + 1]); }
;     const float mx = fmaxf(ma, mb);
;     return fmaxf(mx, __shfl_xor(mx, 32));
; }
; template <int MODE, bool MASK, bool WITH_O>
; DI void attn_tile_t(lptr Kt, lptr Vt, const bf16x8 (&qf)[4], f32x16& o0, f32x16& o1, RowState& rs, const TP& tp, int lane) {
;     const int hi = lane >> 5;
;     f32x16 s0, s1;
;     bias_init<MODE>(s0, s1, tp, tp.fb - rs.mref, hi);
;     qk_acc(Kt, qf, s0, s1, lane);
;     const float mx = mask_rowmax<MASK>(s0, s1, tp);
;     const bool was = rs.seen; rs.seen = was || (mx > -1e29f);
;     const bool trig = (mx > 8.f) || (!was && mx > -1e29f && mx < -8.f);
;     if (__builtin_expect(__any(trig), 0)) {
.LBB0_493:
	s_lshl_b32 s2, s55, 8
	s_add_i32 s26, s2, 0
	s_mul_i32 s2, s55, 0x2300
	s_add_i32 s56, s26, s2
	s_mov_b64 s[2:3], -1
	s_cmp_le_i32 s31, s42
	v_sub_f32_e32 v156, v157, v160
	v_add3_u32 v161, s56, v131, v133
	v_lshl_add_u32 v162, v126, 2, s26
	s_cbranch_scc0 .LBB0_498
	ds_read_b128 v[34:37], v162 offset:36992
	ds_read_b128 v[38:41], v162 offset:36864
	ds_read_b128 v[42:45], v162 offset:36880
	ds_read_b128 v[46:49], v162 offset:37008
	ds_read_b128 v[50:53], v162 offset:36928
	ds_read_b128 v[54:57], v162 offset:37056
	ds_read_b128 v[58:61], v162 offset:36944
	ds_read_b128 v[62:65], v162 offset:37072
	ds_read_b128 v[166:169], v161 offset:4608
	ds_read_b128 v[216:219], v161
	ds_read_b128 v[228:231], v161 offset:32
	ds_read_b128 v[232:235], v161 offset:4640
	ds_read_b128 v[236:239], v161 offset:64
	ds_read_b128 v[240:243], v161 offset:4672
	ds_read_b128 v[244:247], v161 offset:96
	ds_read_b128 v[252:255], v161 offset:4704
	s_waitcnt lgkmcnt(13)
	v_pk_fma_f32 v[88:89], v[44:45], s[80:81], v[156:157] op_sel_hi:[1,0,0]
	s_waitcnt lgkmcnt(11)
	v_pk_fma_f32 v[92:93], v[52:53], s[80:81], v[156:157] op_sel_hi:[1,0,0]
	v_pk_fma_f32 v[84:85], v[40:41], s[80:81], v[156:157] op_sel_hi:[1,0,0]
	s_waitcnt lgkmcnt(9)
	v_pk_fma_f32 v[96:97], v[60:61], s[80:81], v[156:157] op_sel_hi:[1,0,0]
	v_pk_fma_f32 v[94:95], v[58:59], s[80:81], v[156:157] op_sel_hi:[1,0,0]
	v_pk_fma_f32 v[90:91], v[50:51], s[80:81], v[156:157] op_sel_hi:[1,0,0]
	v_pk_fma_f32 v[86:87], v[42:43], s[80:81], v[156:157] op_sel_hi:[1,0,0]
	v_pk_fma_f32 v[82:83], v[38:39], s[80:81], v[156:157] op_sel_hi:[1,0,0]
	s_waitcnt lgkmcnt(8)
	v_pk_fma_f32 v[80:81], v[64:65], s[80:81], v[156:157] op_sel_hi:[1,0,0]
	v_pk_fma_f32 v[76:77], v[56:57], s[80:81], v[156:157] op_sel_hi:[1,0,0]
	v_pk_fma_f32 v[72:73], v[48:49], s[80:81], v[156:157] op_sel_hi:[1,0,0]
	v_pk_fma_f32 v[68:69], v[36:37], s[80:81], v[156:157] op_sel_hi:[1,0,0]
	v_pk_fma_f32 v[78:79], v[62:63], s[80:81], v[156:157] op_sel_hi:[1,0,0]
	v_pk_fma_f32 v[74:75], v[54:55], s[80:81], v[156:157] op_sel_hi:[1,0,0]
	v_pk_fma_f32 v[70:71], v[46:47], s[80:81], v[156:157] op_sel_hi:[1,0,0]
	v_pk_fma_f32 v[66:67], v[34:35], s[80:81], v[156:157] op_sel_hi:[1,0,0]
	s_setprio 1
	s_waitcnt lgkmcnt(6)
	v_mfma_f32_32x32x16_bf16 v[82:97], v[216:219], v[98:101], v[82:97]
	v_mfma_f32_32x32x16_bf16 v[66:81], v[166:169], v[98:101], v[66:81]
	s_waitcnt lgkmcnt(5)
	v_mfma_f32_32x32x16_bf16 v[82:97], v[228:231], v[102:105], v[82:97]
	s_waitcnt lgkmcnt(4)
	v_mfma_f32_32x32x16_bf16 v[66:81], v[232:235], v[102:105], v[66:81]
	s_waitcnt lgkmcnt(3)
	v_mfma_f32_32x32x16_bf16 v[82:97], v[236:239], v[106:109], v[82:97]
	s_waitcnt lgkmcnt(2)
	v_mfma_f32_32x32x16_bf16 v[66:81], v[240:243], v[106:109], v[66:81]
	s_waitcnt lgkmcnt(1)
	v_mfma_f32_32x32x16_bf16 v[82:97], v[244:247], v[110:113], v[82:97]
	s_waitcnt lgkmcnt(0)
	v_mfma_f32_32x32x16_bf16 v[66:81], v[252:255], v[110:113], v[66:81]
	s_setprio 0
	v_add3_u32 v228, s56, v135, v141
	ds_read_b128 v[216:219], v228 offset:18432
	ds_read_b128 v[38:41], v228 offset:23040
	ds_read_b128 v[42:45], v228 offset:18464
	ds_read_b128 v[46:49], v228 offset:23072
	ds_read_b128 v[50:53], v228 offset:18496
	ds_read_b128 v[54:57], v228 offset:23104
	ds_read_b128 v[58:61], v228 offset:18528
	ds_read_b128 v[62:65], v228 offset:23136
	s_nop 1
	v_max_f32_e32 v34, v81, v81
	v_max_f32_e32 v35, v97, v97
	v_min_f32_e32 v34, v35, v34
	v_max3_f32 v35, v34, v82, v66
	v_max3_f32 v34, v34, v83, v67
	v_and_b32_e32 v36, 64, v209
	v_max3_f32 v35, v35, v84, v68
	v_max3_f32 v34, v34, v85, v69
	v_add_u32_e32 v36, 64, v36
	v_max3_f32 v35, v35, v86, v70
	v_max3_f32 v34, v34, v87, v71
	s_mov_b32 s2, 0xefa18f08
	v_max3_f32 v35, v35, v88, v72
	v_max3_f32 v34, v34, v89, v73
	s_mov_b64 s[28:29], -1
	v_max3_f32 v35, v35, v90, v74
	v_max3_f32 v34, v34, v91, v75
	s_nop 0
	v_max3_f32 v35, v35, v92, v76
	v_max3_f32 v34, v34, v93, v77
	s_nop 0
	v_max3_f32 v35, v35, v94, v78
	v_max3_f32 v34, v34, v95, v79
	s_nop 0
	v_max3_f32 v35, v35, v96, v80
	v_max3_f32 v34, v34, v97, v81
	s_nop 0
	v_max_f32_e32 v34, v34, v34
	v_max_f32_e32 v35, v35, v35
	v_max_f32_e32 v34, v35, v34
	v_xor_b32_e32 v35, 32, v209
	v_cmp_lt_i32_e32 vcc, v35, v36
	s_nop 1
	v_cndmask_b32_e32 v35, v209, v35, vcc
	v_lshlrev_b32_e32 v35, 2, v35
	ds_bpermute_b32 v35, v35, v34
	s_waitcnt lgkmcnt(0)
	v_max_f32_e32 v35, v35, v35
	v_max_f32_e32 v165, v34, v35
	v_cmp_lt_f32_e64 s[26:27], s2, v165
	s_mov_b32 s2, 0x41000000
	v_cmp_nlt_f32_e32 vcc, s2, v165
	s_and_saveexec_b64 s[2:3], vcc
	s_mov_b32 s28, 0xc1000000
	v_cmp_gt_f32_e32 vcc, s28, v165
	s_xor_b64 s[28:29], s[22:23], -1
	s_and_b64 s[28:29], vcc, s[28:29]
	s_and_b64 s[28:29], s[26:27], s[28:29]
	s_orn2_b64 s[28:29], s[28:29], exec
	s_or_b64 exec, exec, s[2:3]
	v_cndmask_b32_e64 v34, 0, 1, s[28:29]
	v_cmp_ne_u32_e32 vcc, 0, v34
	v_mov_b32_e32 v163, v160
	v_mov_b32_e32 v164, v159
	s_cbranch_vccnz .LBB0_514
; template <int MODE, bool MASK, bool WITH_O>
; DI void attn_tile_t(lptr Kt, lptr Vt, const bf16x8 (&qf)[4], f32x16& o0, f32x16& o1, RowState& rs, const TP& tp, int lane) {
;     ...
;         const int i = lane & 31;
;         lptr vp = Vt + i * KPB + hi * 16;
;         float sum = 0.f;
;     ...
;         PV_STEP(s0, 0, 0) PV_STEP(s0, 8, 32) PV_STEP(s1, 0, 64) PV_STEP(s1, 8, 96)
;     ...
;         rs.l += sum;
.LBB0_497:
	v_exp_f32_e32 v82, v82
	v_exp_f32_e32 v83, v83
	v_exp_f32_e32 v84, v84
	v_exp_f32_e32 v85, v85
	v_exp_f32_e32 v86, v86
	v_exp_f32_e32 v87, v87
	v_exp_f32_e32 v88, v88
	v_exp_f32_e32 v89, v89
	v_add_f32_e32 v215, 0, v82
	v_add_f32_e32 v215, v83, v215
	v_add_f32_e32 v215, v84, v215
	v_add_f32_e32 v215, v85, v215
	v_cvt_pk_bf16_f32 v82, v82, v83
	v_cvt_pk_bf16_f32 v83, v84, v85
	v_cvt_pk_bf16_f32 v84, v86, v87
	v_cvt_pk_bf16_f32 v85, v88, v89
	v_add_f32_e32 v215, v86, v215
	v_add_f32_e32 v215, v87, v215
	s_waitcnt lgkmcnt(1)
	v_mfma_f32_32x32x16_bf16 v[2:17], v[216:219], v[82:85], v[2:17]
	v_add_f32_e32 v215, v88, v215
	v_add_f32_e32 v215, v89, v215
	s_waitcnt lgkmcnt(0)
	v_mfma_f32_32x32x16_bf16 v[18:33], v[38:41], v[82:85], v[18:33]
	v_exp_f32_e32 v90, v90
	v_exp_f32_e32 v91, v91
	v_exp_f32_e32 v92, v92
	v_exp_f32_e32 v93, v93
	v_exp_f32_e32 v94, v94
	v_exp_f32_e32 v95, v95
	v_exp_f32_e32 v96, v96
	v_exp_f32_e32 v97, v97
	v_add_f32_e32 v166, v90, v215
	v_add_f32_e32 v166, v91, v166
	v_add_f32_e32 v166, v92, v166
	v_add_f32_e32 v166, v93, v166
	v_cvt_pk_bf16_f32 v90, v90, v91
	v_cvt_pk_bf16_f32 v91, v92, v93
	v_cvt_pk_bf16_f32 v92, v94, v95
	v_cvt_pk_bf16_f32 v93, v96, v97
	v_add_f32_e32 v166, v94, v166
	v_add_f32_e32 v166, v95, v166
	s_waitcnt lgkmcnt(1)
	v_mfma_f32_32x32x16_bf16 v[2:17], v[42:45], v[90:93], v[2:17]
	v_add_f32_e32 v166, v96, v166
	v_add_f32_e32 v166, v97, v166
	s_waitcnt lgkmcnt(0)
	v_mfma_f32_32x32x16_bf16 v[18:33], v[46:49], v[90:93], v[18:33]
	v_exp_f32_e32 v66, v66
	v_exp_f32_e32 v67, v67
	v_exp_f32_e32 v68, v68
	v_exp_f32_e32 v69, v69
	v_exp_f32_e32 v70, v70
	v_exp_f32_e32 v71, v71
	v_exp_f32_e32 v72, v72
	v_exp_f32_e32 v73, v73
	v_add_f32_e32 v90, v66, v166
	v_add_f32_e32 v90, v67, v90
	v_add_f32_e32 v90, v68, v90
	v_add_f32_e32 v90, v69, v90
	v_cvt_pk_bf16_f32 v66, v66, v67
	v_cvt_pk_bf16_f32 v67, v68, v69
	v_cvt_pk_bf16_f32 v68, v70, v71
	v_cvt_pk_bf16_f32 v69, v72, v73
	v_add_f32_e32 v90, v70, v90
	v_add_f32_e32 v90, v71, v90
	s_waitcnt lgkmcnt(1)
	v_mfma_f32_32x32x16_bf16 v[2:17], v[50:53], v[66:69], v[2:17]
	v_add_f32_e32 v90, v72, v90
	v_add_f32_e32 v90, v73, v90
	s_waitcnt lgkmcnt(0)
	v_mfma_f32_32x32x16_bf16 v[18:33], v[54:57], v[66:69], v[18:33]
	v_exp_f32_e32 v67, v74
	v_exp_f32_e32 v72, v75
	v_exp_f32_e32 v73, v76
	v_exp_f32_e32 v74, v77
	v_add_f32_e32 v66, v67, v90
	v_exp_f32_e32 v75, v78
	v_exp_f32_e32 v76, v79
	v_exp_f32_e32 v77, v80
	v_exp_f32_e32 v78, v81
	v_add_f32_e32 v66, v72, v66
	v_add_f32_e32 v66, v73, v66
	v_add_f32_e32 v66, v74, v66
	v_add_f32_e32 v66, v75, v66
	v_cvt_pk_bf16_f32 v72, v67, v72
	v_cvt_pk_bf16_f32 v73, v73, v74
	v_cvt_pk_bf16_f32 v74, v75, v76
	v_cvt_pk_bf16_f32 v75, v77, v78
	v_add_f32_e32 v66, v76, v66
	v_add_f32_e32 v66, v77, v66
	s_waitcnt lgkmcnt(1)
	v_mfma_f32_32x32x16_bf16 v[2:17], v[58:61], v[72:75], v[2:17]
	v_add_f32_e32 v66, v78, v66
	s_waitcnt lgkmcnt(0)
	v_mfma_f32_32x32x16_bf16 v[18:33], v[62:65], v[72:75], v[18:33]
	s_mov_b64 s[2:3], 0

; #define LAS __attribute__((address_space(3)))
; #define MFMA32(a, b, c) __builtin_amdgcn_mfma_f32_32x32x16_bf16((a), (b), (c), 0, 0, 0)
; DI void qk_acc(lptr Kt, const bf16x8 (&qf)[4], f32x16& s0, f32x16& s1, int lane) {
;     const int i = lane & 31, hi = lane >> 5;
;     const int krow = (i & 19) | ((i & 4) << 1) | ((i & 8) >> 1);
;     lptr kp = Kt + krow * KPB + hi * 16;
;     bf16x8 a0[4], a1[4];
; #pragma unroll
;     for (int d0 = 0; d0 < 4; ++d0) { a0[d0] = *(LAS bf16x8*)(kp + d0 * 32); a1[d0] = *(LAS bf16x8*)(kp + 32 * KPB + d0 * 32); }
;     __builtin_amdgcn_s_setprio(1);
; #pragma unroll
;     for (int d0 = 0; d0 < 4; ++d0) { s0 = MFMA32(a0[d0], qf[d0], s0); s1 = MFMA32(a1[d0], qf[d0], s1); }
;     __builtin_amdgcn_s_setprio(0);
; }
; DI void slc_unit(const Params& P, lptr L, int u, int tid, int lane, int wid) {
;     ...
;     ATT_LOOP_BEGIN(NTS, false, kb_ + (size_t)((int)list[jt] * 64) * PROJ_LD, vb_ + (size_t)((int)list[jt]) * 64, (const float*)nullptr)
;         const int j = (int)list[jt], kv0 = j * 64;
;         const bool sel = (sm[ql * 8 + (j >> 5)] >> (j & 31)) & 1u;
;         if (__any(sel)) {
;             TP tp; tp.cs = nullptr; tp.sl = sl; tp.fb = sl * (float)(kv0 + 8 * hi - t); tp.lim = t - kv0 - 8 * hi; tp.lim2 = -(1 << 30); tp.sel = sel;
;             attn_tile<1>(Kt, Vt, qf, o0, o1, rs, tp, true, lane);
.LBB0_613:
	s_add_i32 s1, s0, 0
	s_add_i32 s1, s1, 0x1a104
	v_mov_b32_e32 v0, s1
	ds_read_u8 v0, v0
	s_and_b32 s31, s0, 1
	s_waitcnt lgkmcnt(0)
	v_lshrrev_b32_e32 v34, 3, v0
	v_and_b32_e32 v34, 28, v34
	v_add_u32_e32 v34, v186, v34
	ds_read_b32 v34, v34
	v_and_b32_e32 v35, 31, v0
	s_waitcnt lgkmcnt(0)
	v_lshrrev_b32_e32 v36, v0, v34
	v_bfe_u32 v34, v34, v35, 1
	v_and_b32_e32 v35, 1, v36
	v_cmp_ne_u32_e32 vcc, 0, v34
	v_cmp_eq_u32_e64 s[28:29], 1, v35
	s_cbranch_vccz .LBB0_618
	s_mul_i32 s33, s31, 0x2400
	v_add_u32_e32 v241, s33, v170
	ds_read_b128 v[102:105], v241 offset:4608
	ds_read_b128 v[106:109], v241
	ds_read_b128 v[110:113], v241 offset:32
	ds_read_b128 v[114:117], v241 offset:4640
	ds_read_b128 v[118:121], v241 offset:64
	ds_read_b128 v[158:161], v241 offset:4672
	ds_read_b128 v[162:165], v241 offset:96
	ds_read_b128 v[166:169], v241 offset:4704
	v_lshl_or_b32 v0, v0, 6, v126
	v_sub_u32_e32 v34, v0, v91
	v_cvt_f32_i32_e32 v34, v34
	s_mov_b32 s0, 2.0
	v_sub_u32_e32 v152, v91, v0
	s_mov_b32 s1, 0x40400000
	v_cmp_lt_i32_e32 vcc, 54, v152
	v_fma_f32 v0, v150, v34, -v101
	s_cmp_eq_u64 vcc, exec
	s_cselect_b64 s[98:99], -1, 0
	s_orn2_b64 s[100:101], s[28:29], s[98:99]
	v_cndmask_b32_e64 v0, v210, v0, s[100:101]
	v_pk_fma_f32 v[36:37], v[94:95], s[0:1], v[0:1] op_sel_hi:[1,1,0]
	s_mov_b32 s0, 4.0
	s_mov_b32 s1, 0x40a00000
	v_pk_fma_f32 v[38:39], v[94:95], s[0:1], v[0:1] op_sel_hi:[1,1,0]
	s_mov_b32 s0, 0x40c00000
	s_mov_b32 s1, 0x40e00000
	v_pk_fma_f32 v[40:41], v[94:95], s[0:1], v[0:1] op_sel_hi:[1,1,0]
	s_mov_b32 s0, 0x41800000
	s_mov_b32 s1, 0x41880000
	v_pk_fma_f32 v[42:43], v[94:95], s[0:1], v[0:1] op_sel_hi:[1,1,0]
	s_mov_b32 s0, 0x41900000
	s_mov_b32 s1, 0x41980000
	v_pk_fma_f32 v[44:45], v[94:95], s[0:1], v[0:1] op_sel_hi:[1,1,0]
	s_mov_b32 s0, 0x41a00000
	s_mul_i32 s33, s31, 0x2400
	s_mov_b32 s1, 0x41a80000
	v_mov_b32_e32 v151, v150
	v_fma_f32 v34, 0, v150, v0
	v_add_f32_e32 v35, v150, v0
	v_pk_fma_f32 v[46:47], v[94:95], s[0:1], v[0:1] op_sel_hi:[1,1,0]
	v_pk_fma_f32 v[48:49], v[94:95], s[18:19], v[0:1] op_sel_hi:[1,1,0]
	v_pk_fma_f32 v[64:65], v[150:151], s[4:5], v[0:1] op_sel_hi:[1,1,0]
	v_pk_fma_f32 v[62:63], v[150:151], s[14:15], v[0:1] op_sel_hi:[1,1,0]
	v_pk_fma_f32 v[60:61], v[150:151], s[16:17], v[0:1] op_sel_hi:[1,1,0]
	v_pk_fma_f32 v[58:59], v[150:151], s[94:95], v[0:1] op_sel_hi:[1,1,0]
	v_pk_fma_f32 v[56:57], v[150:151], s[96:97], v[0:1] op_sel_hi:[1,1,0]
	v_pk_fma_f32 v[54:55], v[150:151], s[84:85], v[0:1] op_sel_hi:[1,1,0]
	v_pk_fma_f32 v[52:53], v[150:151], s[72:73], v[0:1] op_sel_hi:[1,1,0]
	v_pk_fma_f32 v[50:51], v[96:97], s[44:45], v[0:1] op_sel_hi:[1,1,0]
	s_setprio 1
	s_waitcnt lgkmcnt(6)
	v_mfma_f32_32x32x16_bf16 v[34:49], v[106:109], v[66:69], v[34:49]
	v_mfma_f32_32x32x16_bf16 v[50:65], v[102:105], v[66:69], v[50:65]
	s_waitcnt lgkmcnt(5)
	v_mfma_f32_32x32x16_bf16 v[34:49], v[110:113], v[70:73], v[34:49]
	s_waitcnt lgkmcnt(4)
	v_mfma_f32_32x32x16_bf16 v[50:65], v[114:117], v[70:73], v[50:65]
	s_waitcnt lgkmcnt(3)
	v_mfma_f32_32x32x16_bf16 v[34:49], v[118:121], v[74:77], v[34:49]
	s_waitcnt lgkmcnt(2)
	v_mfma_f32_32x32x16_bf16 v[50:65], v[158:161], v[74:77], v[50:65]
	s_waitcnt lgkmcnt(1)
	v_mfma_f32_32x32x16_bf16 v[34:49], v[162:165], v[78:81], v[34:49]
	s_waitcnt lgkmcnt(0)
	v_mfma_f32_32x32x16_bf16 v[50:65], v[166:169], v[78:81], v[50:65]
	s_setprio 0
	v_add_u32_e32 v240, s33, v172
	ds_read_b128 v[228:231], v240 offset:18432
	ds_read_b128 v[232:235], v240 offset:23040
	ds_read_b128 v[236:239], v240 offset:18464
	ds_read_b128 v[114:117], v240 offset:23072
	ds_read_b128 v[118:121], v240 offset:18496
	ds_read_b128 v[158:161], v240 offset:23104
	ds_read_b128 v[162:165], v240 offset:18528
	ds_read_b128 v[166:169], v240 offset:23136
	s_and_b64 vcc, exec, s[98:99]
	s_cbranch_vccz .Lslc_masked
	v_mov_b32_e32 v106, v34
	v_mov_b32_e32 v102, v50
	v_mov_b32_e32 v103, v35
	v_mov_b32_e32 v104, v36
	v_mov_b32_e32 v50, v52
	v_mov_b32_e32 v105, v37
	v_mov_b32_e32 v52, v53
	v_mov_b32_e32 v107, v38
	v_mov_b32_e32 v53, v54
	v_mov_b32_e32 v108, v39
	v_mov_b32_e32 v54, v55
	v_mov_b32_e32 v109, v40
	v_mov_b32_e32 v55, v56
	v_mov_b32_e32 v110, v41
	v_mov_b32_e32 v41, v57
	v_mov_b32_e32 v56, v42
	v_mov_b32_e32 v38, v58
	v_mov_b32_e32 v34, v59
	v_mov_b32_e32 v42, v44
	v_mov_b32_e32 v0, v60
	v_mov_b32_e32 v44, v45
	v_mov_b32_e32 v35, v61
	v_mov_b32_e32 v45, v46
	v_mov_b32_e32 v36, v62
	v_mov_b32_e32 v46, v47
	v_mov_b32_e32 v37, v63
	v_mov_b32_e32 v47, v48
	v_mov_b32_e32 v39, v64
	v_mov_b32_e32 v48, v49
	v_mov_b32_e32 v40, v65
	s_branch .Lslc_join

; template <int MODE, bool MASK, bool WITH_O>
; DI void attn_tile_t(lptr Kt, lptr Vt, const bf16x8 (&qf)[4], f32x16& o0, f32x16& o1, RowState& rs, const TP& tp, int lane) {
;     ...
;         const int i = lane & 31;
;         lptr vp = Vt + i * KPB + hi * 16;
;         float sum = 0.f;
;     ...
;         PV_STEP(s0, 0, 0) PV_STEP(s0, 8, 32) PV_STEP(s1, 0, 64) PV_STEP(s1, 8, 96)
;     ...
;         rs.l += sum;
.LBB0_617:
	v_exp_f32_e32 v49, v106
	v_exp_f32_e32 v103, v103
	v_exp_f32_e32 v111, v104
	v_exp_f32_e32 v105, v105
	v_add_f32_e32 v106, 0, v49
	v_add_f32_e32 v106, v103, v106
	v_add_f32_e32 v104, v111, v106
	v_exp_f32_e32 v106, v107
	v_exp_f32_e32 v107, v108
	v_exp_f32_e32 v108, v109
	v_add_f32_e32 v104, v105, v104
	v_exp_f32_e32 v109, v110
	v_add_f32_e32 v104, v106, v104
	v_add_f32_e32 v104, v107, v104
	v_add_f32_e32 v104, v108, v104
	v_add_f32_e32 v110, v109, v104
	v_cvt_pk_bf16_f32 v104, v49, v103
	v_cvt_pk_bf16_f32 v105, v111, v105
	v_cvt_pk_bf16_f32 v106, v106, v107
	v_cvt_pk_bf16_f32 v107, v108, v109
	s_or_b64 s[22:23], s[22:23], s[28:29]
	s_waitcnt lgkmcnt(1)
	v_mfma_f32_32x32x16_bf16 v[18:33], v[228:231], v[104:107], v[18:33]
	s_waitcnt lgkmcnt(0)
	v_mfma_f32_32x32x16_bf16 v[2:17], v[232:235], v[104:107], v[2:17]
	v_exp_f32_e32 v49, v56
	v_exp_f32_e32 v43, v43
	v_exp_f32_e32 v103, v42
	v_exp_f32_e32 v44, v44
	v_add_f32_e32 v56, v49, v110
	v_exp_f32_e32 v45, v45
	v_add_f32_e32 v56, v43, v56
	v_exp_f32_e32 v46, v46
	v_add_f32_e32 v42, v103, v56
	v_exp_f32_e32 v47, v47
	v_add_f32_e32 v42, v44, v42
	v_exp_f32_e32 v48, v48
	v_add_f32_e32 v42, v45, v42
	v_add_f32_e32 v42, v46, v42
	v_add_f32_e32 v42, v47, v42
	v_add_f32_e32 v56, v48, v42
	v_cvt_pk_bf16_f32 v42, v49, v43
	v_cvt_pk_bf16_f32 v43, v103, v44
	v_cvt_pk_bf16_f32 v44, v45, v46
	v_cvt_pk_bf16_f32 v45, v47, v48
	s_waitcnt lgkmcnt(1)
	s_nop 0
	v_mfma_f32_32x32x16_bf16 v[18:33], v[236:239], v[42:45], v[18:33]
	s_waitcnt lgkmcnt(0)
	v_mfma_f32_32x32x16_bf16 v[2:17], v[114:117], v[42:45], v[2:17]
	v_exp_f32_e32 v58, v102
	v_exp_f32_e32 v51, v51
	v_exp_f32_e32 v59, v50
	v_exp_f32_e32 v52, v52
	v_add_f32_e32 v56, v58, v56
	v_exp_f32_e32 v53, v53
	v_add_f32_e32 v56, v51, v56
	v_exp_f32_e32 v54, v54
	v_add_f32_e32 v50, v59, v56
	v_exp_f32_e32 v55, v55
	v_add_f32_e32 v50, v52, v50
	v_exp_f32_e32 v41, v41
	v_add_f32_e32 v50, v53, v50
	v_add_f32_e32 v50, v54, v50
	v_add_f32_e32 v50, v55, v50
	v_add_f32_e32 v56, v41, v50
	v_cvt_pk_bf16_f32 v50, v58, v51
	v_cvt_pk_bf16_f32 v51, v59, v52
	v_cvt_pk_bf16_f32 v52, v53, v54
	v_cvt_pk_bf16_f32 v53, v55, v41
	s_waitcnt lgkmcnt(1)
	s_nop 0
	v_mfma_f32_32x32x16_bf16 v[18:33], v[118:121], v[50:53], v[18:33]
	s_waitcnt lgkmcnt(0)
	v_mfma_f32_32x32x16_bf16 v[2:17], v[158:161], v[50:53], v[2:17]
	v_exp_f32_e32 v38, v38
	v_exp_f32_e32 v34, v34
	v_exp_f32_e32 v0, v0
	v_exp_f32_e32 v35, v35
	v_add_f32_e32 v41, v38, v56
	v_exp_f32_e32 v36, v36
	v_add_f32_e32 v41, v34, v41
	v_exp_f32_e32 v37, v37
	v_exp_f32_e32 v39, v39
	v_exp_f32_e32 v40, v40
	v_add_f32_e32 v41, v0, v41
	v_add_f32_e32 v41, v35, v41
	v_add_f32_e32 v41, v36, v41
	v_add_f32_e32 v41, v37, v41
	v_cvt_pk_bf16_f32 v34, v38, v34
	v_cvt_pk_bf16_f32 v35, v0, v35
	v_cvt_pk_bf16_f32 v36, v36, v37
	v_cvt_pk_bf16_f32 v37, v39, v40
	v_add_f32_e32 v41, v39, v41
	v_add_f32_e32 v41, v40, v41
	s_waitcnt lgkmcnt(1)
	v_mfma_f32_32x32x16_bf16 v[18:33], v[162:165], v[34:37], v[18:33]
	s_waitcnt lgkmcnt(0)
	v_mfma_f32_32x32x16_bf16 v[2:17], v[166:169], v[34:37], v[2:17]
	v_add_f32_e32 v100, v100, v41
